# attention unit epilogue de-serialised: 16 li_l reads + rcp hoisted up front, 4 ds_read_b128 per column half issued together (on top of v63 gemv0b)
# speedup vs baseline: 1.0049x; 1.0049x over previous
; #define SBAR() __builtin_amdgcn_sched_barrier(0)
; __device__ __forceinline__ void pv_d0(f32x16* o, int vb, bf16x8 pa0, bf16x8 pa1, bf16x8 pa2, bf16x8 pa3) {
;   VFrag fa, fb;
;   v_read8<0>(fa, vb); v_read8<1>(fb, vb);
;   asm volatile("s_waitcnt lgkmcnt(8)" ::: "memory"); SBAR(); pv_mma(o[0], fa, pa0, pa1, pa2, pa3); SBAR();
;   v_read8<2>(fa, vb);
;   asm volatile("s_waitcnt lgkmcnt(8)" ::: "memory"); SBAR(); pv_mma(o[1], fb, pa0, pa1, pa2, pa3); SBAR();
;   v_read8<3>(fb, vb);
;   asm volatile("s_waitcnt lgkmcnt(8)" ::: "memory"); SBAR(); pv_mma(o[2], fa, pa0, pa1, pa2, pa3); SBAR();
;   asm volatile("s_waitcnt lgkmcnt(0)" ::: "memory"); SBAR(); pv_mma(o[3], fb, pa0, pa1, pa2, pa3); SBAR();
; }
.LBB0_1090:
	s_cmp_eq_u32 s70, 0
	s_cbranch_scc1 .LBB0_1094
	s_add_i32 s4, s70, -1
	s_mul_i32 s4, s4, s63
	s_add_i32 s4, s4, s46
	s_lshl_b32 s5, s4, 4
	s_lshl_b32 s4, s4, 8
	s_and_b32 s6, s5, 0xfffff800
	s_and_b32 s4, s4, 0x700
	s_or_b32 s4, s6, s4
	v_add_u32_e32 v34, s4, v210
	v_ashrrev_i32_e32 v35, 31, v34
	v_lshlrev_b64 v[46:47], 11, v[34:35]
	s_and_b32 s4, s5, 0x780
	v_or_b32_e32 v33, s4, v46
	v_or_b32_e32 v46, v33, v184
	v_lshl_add_u64 v[34:35], v[46:47], 1, s[14:15]
	v_add_co_u32_e32 v36, vcc, s62, v34
	v_lshl_add_u32 v33, s72, 14, v209
	s_nop 0
	v_addc_co_u32_e32 v37, vcc, 0, v35, vcc
	v_add_co_u32_e32 v38, vcc, s64, v34
	s_nop 1
	v_addc_co_u32_e32 v39, vcc, 0, v35, vcc
	v_add_co_u32_e32 v214, vcc, s66, v34
	s_nop 1
	v_addc_co_u32_e32 v215, vcc, 0, v35, vcc
	global_load_dwordx4 v[160:163], v[34:35], off
	global_load_dwordx4 v[80:83], v[34:35], off offset:128
	global_load_dwordx4 v[108:111], v[36:37], off
	global_load_dwordx4 v[42:45], v[36:37], off offset:128
	global_load_dwordx4 v[104:107], v[38:39], off
	s_nop 0
	global_load_dwordx4 v[38:41], v[38:39], off offset:128
	s_nop 0
	global_load_dwordx4 v[100:103], v[214:215], off
	global_load_dwordx4 v[34:37], v[214:215], off offset:128
	ds_read_b64_tr_b16 v[214:215], v33 offset:0
	ds_read_b64_tr_b16 v[216:217], v33 offset:0x800
	ds_read_b64_tr_b16 v[218:219], v33 offset:0x1000
	ds_read_b64_tr_b16 v[220:221], v33 offset:0x1800
	ds_read_b64_tr_b16 v[222:223], v33 offset:0x2000
	ds_read_b64_tr_b16 v[224:225], v33 offset:0x2800
	ds_read_b64_tr_b16 v[226:227], v33 offset:0x3000
	ds_read_b64_tr_b16 v[228:229], v33 offset:0x3800
	ds_read_b64_tr_b16 v[230:231], v33 offset:0x200
	ds_read_b64_tr_b16 v[232:233], v33 offset:0xa00
	ds_read_b64_tr_b16 v[234:235], v33 offset:0x1200
	ds_read_b64_tr_b16 v[236:237], v33 offset:0x1a00
	ds_read_b64_tr_b16 v[238:239], v33 offset:0x2200
	ds_read_b64_tr_b16 v[240:241], v33 offset:0x2a00
	ds_read_b64_tr_b16 v[242:243], v33 offset:0x3200
	ds_read_b64_tr_b16 v[244:245], v33 offset:0x3a00
	s_waitcnt lgkmcnt(8)
	s_nop 0
	v_mfma_f32_32x32x16_bf16 v[64:79], v[96:99], v[214:217], v[64:79]
	v_mfma_f32_32x32x16_bf16 v[64:79], v[92:95], v[218:221], v[64:79]
	v_mfma_f32_32x32x16_bf16 v[64:79], v[88:91], v[222:225], v[64:79]
	v_mfma_f32_32x32x16_bf16 v[64:79], v[84:87], v[226:229], v[64:79]
	ds_read_b64_tr_b16 v[214:215], v33 offset:0x400
	ds_read_b64_tr_b16 v[216:217], v33 offset:0xc00
	ds_read_b64_tr_b16 v[218:219], v33 offset:0x1400
	ds_read_b64_tr_b16 v[220:221], v33 offset:0x1c00
	ds_read_b64_tr_b16 v[222:223], v33 offset:0x2400
	ds_read_b64_tr_b16 v[224:225], v33 offset:0x2c00
	ds_read_b64_tr_b16 v[226:227], v33 offset:0x3400
	ds_read_b64_tr_b16 v[228:229], v33 offset:0x3c00
	s_waitcnt lgkmcnt(8)
	v_mfma_f32_32x32x16_bf16 v[48:63], v[96:99], v[230:233], v[48:63]
	v_mfma_f32_32x32x16_bf16 v[48:63], v[92:95], v[234:237], v[48:63]
	v_mfma_f32_32x32x16_bf16 v[48:63], v[88:91], v[238:241], v[48:63]
	v_mfma_f32_32x32x16_bf16 v[48:63], v[84:87], v[242:245], v[48:63]
	ds_read_b64_tr_b16 v[230:231], v33 offset:0x600
	ds_read_b64_tr_b16 v[232:233], v33 offset:0xe00
	ds_read_b64_tr_b16 v[234:235], v33 offset:0x1600
	ds_read_b64_tr_b16 v[236:237], v33 offset:0x1e00
	ds_read_b64_tr_b16 v[238:239], v33 offset:0x2600
	ds_read_b64_tr_b16 v[240:241], v33 offset:0x2e00
	ds_read_b64_tr_b16 v[242:243], v33 offset:0x3600
	ds_read_b64_tr_b16 v[244:245], v33 offset:0x3e00
	s_waitcnt lgkmcnt(8)
	v_mfma_f32_32x32x16_bf16 v[16:31], v[96:99], v[214:217], v[16:31]
	v_mfma_f32_32x32x16_bf16 v[16:31], v[92:95], v[218:221], v[16:31]
	v_mfma_f32_32x32x16_bf16 v[16:31], v[88:91], v[222:225], v[16:31]
	v_mfma_f32_32x32x16_bf16 v[16:31], v[84:87], v[226:229], v[16:31]
	s_waitcnt lgkmcnt(0)
	v_mfma_f32_32x32x16_bf16 v[0:15], v[96:99], v[230:233], v[0:15]
	v_mfma_f32_32x32x16_bf16 v[0:15], v[92:95], v[234:237], v[0:15]
	v_mfma_f32_32x32x16_bf16 v[0:15], v[88:91], v[238:241], v[0:15]
	v_mfma_f32_32x32x16_bf16 v[0:15], v[84:87], v[242:245], v[0:15]
	s_and_saveexec_b64 s[4:5], s[0:1]
	ds_write_b32 v208, v187
	s_or_b64 exec, exec, s[4:5]
	s_waitcnt lgkmcnt(0)
	ds_read_b32 v230, v185
	ds_read_b32 v231, v185 offset:4
	ds_read_b32 v232, v185 offset:8
	ds_read_b32 v233, v185 offset:12
	ds_read_b32 v234, v185 offset:32
	ds_read_b32 v235, v185 offset:36
	ds_read_b32 v236, v185 offset:40
	ds_read_b32 v237, v185 offset:44
	ds_read_b32 v238, v185 offset:64
	ds_read_b32 v239, v185 offset:68
	ds_read_b32 v240, v185 offset:72
	ds_read_b32 v241, v185 offset:76
	ds_read_b32 v242, v185 offset:96
	ds_read_b32 v243, v185 offset:100
	ds_read_b32 v244, v185 offset:104
	ds_read_b32 v245, v185 offset:108
	s_waitcnt lgkmcnt(0)
	v_rcp_f32_e32 v230, v230
	v_rcp_f32_e32 v231, v231
	v_rcp_f32_e32 v232, v232
	v_rcp_f32_e32 v233, v233
	v_rcp_f32_e32 v234, v234
	v_rcp_f32_e32 v235, v235
	v_rcp_f32_e32 v236, v236
	v_rcp_f32_e32 v237, v237
	v_rcp_f32_e32 v238, v238
	v_rcp_f32_e32 v239, v239
	v_rcp_f32_e32 v240, v240
	v_rcp_f32_e32 v241, v241
	v_rcp_f32_e32 v242, v242
	v_rcp_f32_e32 v243, v243
	v_rcp_f32_e32 v244, v244
	v_rcp_f32_e32 v245, v245
	s_nop 0
	v_add_u32_e32 v84, v190, v207
	v_lshl_add_u64 v[46:47], v[46:47], 1, s[18:19]
	v_mov_b32_e32 v187, 0
	s_nop 0
	v_mul_f32_e32 v64, v64, v230
	v_mul_f32_e32 v33, v48, v230
	v_cvt_pk_bf16_f32 v48, v64, v32
	ds_write_b16 v84, v48
	v_cvt_pk_bf16_f32 v33, v33, v32
	ds_write_b16 v84, v33 offset:64
	v_add_u32_e32 v64, v190, v206
	s_nop 0
	v_mul_f32_e32 v33, v65, v231
	v_mul_f32_e32 v48, v49, v231
	v_cvt_pk_bf16_f32 v33, v33, v32
	ds_write_b16 v64, v33
	v_cvt_pk_bf16_f32 v33, v48, v32
	ds_write_b16 v64, v33 offset:64
	v_add_u32_e32 v65, v190, v205
	s_nop 0
	v_mul_f32_e32 v33, v66, v232
	v_mul_f32_e32 v48, v50, v232
	v_cvt_pk_bf16_f32 v33, v33, v32
	ds_write_b16 v65, v33
	v_cvt_pk_bf16_f32 v33, v48, v32
	ds_write_b16 v65, v33 offset:64
	v_add_u32_e32 v66, v190, v204
	s_nop 0
	v_mul_f32_e32 v33, v67, v233
	v_mul_f32_e32 v48, v51, v233
	v_cvt_pk_bf16_f32 v33, v33, v32
	ds_write_b16 v66, v33
	v_cvt_pk_bf16_f32 v33, v48, v32
	ds_write_b16 v66, v33 offset:64
	v_add_u32_e32 v67, v190, v203
	s_nop 0
	v_mul_f32_e32 v33, v68, v234
	v_mul_f32_e32 v48, v52, v234
	v_cvt_pk_bf16_f32 v33, v33, v32
	ds_write_b16 v67, v33
	v_cvt_pk_bf16_f32 v33, v48, v32
	ds_write_b16 v67, v33 offset:64
	v_add_u32_e32 v68, v190, v202
	s_waitcnt vmcnt(0)
	v_lshlrev_b32_e32 v52, 16, v160
	s_nop 0
	v_mul_f32_e32 v33, v69, v235
	v_mul_f32_e32 v48, v53, v235
	v_cvt_pk_bf16_f32 v33, v33, v32
	ds_write_b16 v68, v33
	v_cvt_pk_bf16_f32 v33, v48, v32
	ds_write_b16 v68, v33 offset:64
	v_add_u32_e32 v69, v190, v201
	v_and_b32_e32 v53, 0xffff0000, v160
	v_mov_b32_e32 v160, 0xf149f2ca
	s_nop 0
	v_mul_f32_e32 v33, v70, v236
	v_mul_f32_e32 v48, v54, v236
	v_cvt_pk_bf16_f32 v33, v33, v32
	ds_write_b16 v69, v33
	v_cvt_pk_bf16_f32 v33, v48, v32
	ds_write_b16 v69, v33 offset:64
	v_add_u32_e32 v70, v190, v200
	v_lshlrev_b32_e32 v54, 16, v161
	s_nop 0
	v_mul_f32_e32 v33, v71, v237
	v_mul_f32_e32 v48, v55, v237
	v_cvt_pk_bf16_f32 v33, v33, v32
	ds_write_b16 v70, v33
	v_cvt_pk_bf16_f32 v33, v48, v32
	ds_write_b16 v70, v33 offset:64
	v_add_u32_e32 v71, v190, v199
	v_and_b32_e32 v55, 0xffff0000, v161
	s_nop 0
	v_mul_f32_e32 v33, v72, v238
	v_mul_f32_e32 v48, v56, v238
	v_cvt_pk_bf16_f32 v33, v33, v32
	ds_write_b16 v71, v33
	v_cvt_pk_bf16_f32 v33, v48, v32
	ds_write_b16 v71, v33 offset:64
	v_add_u32_e32 v72, v190, v197
	v_lshlrev_b32_e32 v56, 16, v162
	s_nop 0
	v_mul_f32_e32 v33, v73, v239
	v_mul_f32_e32 v48, v57, v239
	v_cvt_pk_bf16_f32 v33, v33, v32
	ds_write_b16 v72, v33
	v_cvt_pk_bf16_f32 v33, v48, v32
	ds_write_b16 v72, v33 offset:64
	v_add_u32_e32 v73, v190, v196
	v_and_b32_e32 v57, 0xffff0000, v162
	s_nop 0
	v_mul_f32_e32 v33, v74, v240
	v_mul_f32_e32 v48, v58, v240
	v_cvt_pk_bf16_f32 v33, v33, v32
	ds_write_b16 v73, v33
	v_cvt_pk_bf16_f32 v33, v48, v32
	ds_write_b16 v73, v33 offset:64
	v_add_u32_e32 v74, v190, v195
	v_and_b32_e32 v58, 0xffff0000, v163
	s_nop 0
	v_mul_f32_e32 v33, v75, v241
	v_mul_f32_e32 v48, v59, v241
	v_cvt_pk_bf16_f32 v33, v33, v32
	ds_write_b16 v74, v33
	v_cvt_pk_bf16_f32 v33, v48, v32
	ds_write_b16 v74, v33 offset:64
	v_add_u32_e32 v75, v190, v194
	s_waitcnt vmcnt(5)
	v_lshlrev_b32_e32 v59, 16, v108
	s_nop 0
	v_mul_f32_e32 v33, v76, v242
	v_mul_f32_e32 v48, v60, v242
	v_cvt_pk_bf16_f32 v33, v33, v32
	ds_write_b16 v75, v33
	v_cvt_pk_bf16_f32 v33, v48, v32
	ds_write_b16 v75, v33 offset:64
	v_add_u32_e32 v60, v190, v193
	v_add_u32_e32 v76, v190, v191
	s_nop 0
	v_mul_f32_e32 v33, v77, v243
	v_mul_f32_e32 v48, v61, v243
	v_cvt_pk_bf16_f32 v33, v33, v32
	ds_write_b16 v60, v33
	v_cvt_pk_bf16_f32 v33, v48, v32
	ds_write_b16 v60, v33 offset:64
	v_add_u32_e32 v61, v190, v192
	v_add_u32_e32 v77, v188, v189
	s_nop 0
	v_mul_f32_e32 v33, v78, v244
	v_mul_f32_e32 v48, v62, v244
	v_cvt_pk_bf16_f32 v33, v33, v32
	ds_write_b16 v61, v33
	v_cvt_pk_bf16_f32 v33, v48, v32
	ds_write_b16 v61, v33 offset:64
	v_and_b32_e32 v62, 0xffff0000, v108
	s_nop 0
	v_mul_f32_e32 v33, v79, v245
	v_cvt_pk_bf16_f32 v33, v33, v32
	v_mul_f32_e32 v48, v63, v245
	ds_write_b16 v76, v33
	v_cvt_pk_bf16_f32 v33, v48, v32
	ds_write_b16 v76, v33 offset:64
	s_waitcnt lgkmcnt(0)
	ds_read_b128 v[214:217], v77
	ds_read_b128 v[218:221], v77 offset:1024
	ds_read_b128 v[222:225], v77 offset:2048
	ds_read_b128 v[226:229], v77 offset:3072
	v_lshlrev_b32_e32 v33, 16, v163
	s_waitcnt lgkmcnt(0)
	v_lshlrev_b32_e32 v63, 16, v214
	v_and_b32_e32 v48, 0xffff0000, v214
	v_lshlrev_b32_e32 v78, 16, v215
	v_and_b32_e32 v49, 0xffff0000, v215
	v_lshlrev_b32_e32 v79, 16, v216
	v_and_b32_e32 v50, 0xffff0000, v216
	v_lshlrev_b32_e32 v85, 16, v217
	v_and_b32_e32 v51, 0xffff0000, v217
	v_mul_f32_e32 v52, v63, v52
	v_mul_f32_e32 v48, v48, v53
	v_mul_f32_e32 v53, v78, v54
	v_mul_f32_e32 v49, v49, v55
	v_mul_f32_e32 v54, v79, v56
	v_mul_f32_e32 v50, v50, v57
	v_mul_f32_e32 v51, v51, v58
	v_mul_f32_e32 v33, v85, v33
	v_cvt_pk_bf16_f32 v48, v52, v48
	v_cvt_pk_bf16_f32 v49, v53, v49
	v_cvt_pk_bf16_f32 v50, v54, v50
	v_cvt_pk_bf16_f32 v51, v33, v51
	global_store_dwordx4 v[46:47], v[48:51], off
	v_lshlrev_b32_e32 v33, 16, v109
	v_and_b32_e32 v56, 0xffff0000, v109
	v_lshlrev_b32_e32 v57, 16, v110
	s_waitcnt lgkmcnt(0)
	v_lshlrev_b32_e32 v48, 16, v218
	v_and_b32_e32 v49, 0xffff0000, v218
	v_lshlrev_b32_e32 v50, 16, v219
	v_and_b32_e32 v51, 0xffff0000, v219
	v_mul_f32_e32 v48, v48, v59
	v_mul_f32_e32 v49, v49, v62
	v_lshlrev_b32_e32 v52, 16, v220
	v_mul_f32_e32 v33, v50, v33
	v_mul_f32_e32 v51, v51, v56
	v_cvt_pk_bf16_f32 v50, v48, v49
	v_and_b32_e32 v48, 0xffff0000, v220
	v_and_b32_e32 v49, 0xffff0000, v110
	v_cvt_pk_bf16_f32 v51, v33, v51
	v_mul_f32_e32 v33, v52, v57
	v_mul_f32_e32 v48, v48, v49
	v_cvt_pk_bf16_f32 v52, v33, v48
	v_lshlrev_b32_e32 v33, 16, v111
	v_lshlrev_b32_e32 v48, 16, v221
	v_mul_f32_e32 v33, v48, v33
	v_and_b32_e32 v48, 0xffff0000, v221
	v_and_b32_e32 v49, 0xffff0000, v111
	v_mul_f32_e32 v48, v48, v49
	v_cvt_pk_bf16_f32 v53, v33, v48
	v_add_co_u32_e32 v48, vcc, s62, v46
	s_waitcnt vmcnt(4)
	v_lshlrev_b32_e32 v33, 16, v104
	v_addc_co_u32_e32 v49, vcc, 0, v47, vcc
	global_store_dwordx4 v[48:49], v[50:53], off
	s_waitcnt lgkmcnt(0)
	s_nop 0
	v_lshlrev_b32_e32 v50, 16, v222
	v_mul_f32_e32 v33, v50, v33
	v_and_b32_e32 v50, 0xffff0000, v222
	v_and_b32_e32 v51, 0xffff0000, v104
	v_mul_f32_e32 v50, v50, v51
	v_cvt_pk_bf16_f32 v52, v33, v50
	v_lshlrev_b32_e32 v33, 16, v105
	v_lshlrev_b32_e32 v50, 16, v223
	v_mul_f32_e32 v33, v50, v33
	v_and_b32_e32 v50, 0xffff0000, v223
	v_and_b32_e32 v51, 0xffff0000, v105
	v_mul_f32_e32 v50, v50, v51
	v_cvt_pk_bf16_f32 v53, v33, v50
	v_lshlrev_b32_e32 v33, 16, v106
	v_lshlrev_b32_e32 v50, 16, v224
	v_mul_f32_e32 v33, v50, v33
	v_and_b32_e32 v50, 0xffff0000, v224
	v_and_b32_e32 v51, 0xffff0000, v106
	v_mul_f32_e32 v50, v50, v51
	v_cvt_pk_bf16_f32 v54, v33, v50
	v_lshlrev_b32_e32 v33, 16, v107
	v_lshlrev_b32_e32 v50, 16, v225
	v_mul_f32_e32 v33, v50, v33
	v_and_b32_e32 v50, 0xffff0000, v225
	v_and_b32_e32 v51, 0xffff0000, v107
	v_mul_f32_e32 v50, v50, v51
	v_cvt_pk_bf16_f32 v55, v33, v50
	v_add_co_u32_e32 v50, vcc, s64, v46
	s_waitcnt vmcnt(3)
	v_lshlrev_b32_e32 v33, 16, v100
	v_addc_co_u32_e32 v51, vcc, 0, v47, vcc
	global_store_dwordx4 v[50:51], v[52:55], off
	s_waitcnt lgkmcnt(0)
	s_nop 0
	v_lshlrev_b32_e32 v52, 16, v226
	v_mul_f32_e32 v33, v52, v33
	v_and_b32_e32 v52, 0xffff0000, v226
	v_and_b32_e32 v53, 0xffff0000, v100
	v_mul_f32_e32 v52, v52, v53
	v_cvt_pk_bf16_f32 v54, v33, v52
	v_lshlrev_b32_e32 v33, 16, v101
	v_lshlrev_b32_e32 v52, 16, v227
	v_mul_f32_e32 v33, v52, v33
	v_and_b32_e32 v52, 0xffff0000, v227
	v_and_b32_e32 v53, 0xffff0000, v101
	v_mul_f32_e32 v52, v52, v53
	v_cvt_pk_bf16_f32 v55, v33, v52
	v_lshlrev_b32_e32 v33, 16, v102
	v_lshlrev_b32_e32 v52, 16, v228
	v_mul_f32_e32 v33, v52, v33
	v_and_b32_e32 v52, 0xffff0000, v228
	v_and_b32_e32 v53, 0xffff0000, v102
	v_mul_f32_e32 v52, v52, v53
	v_cvt_pk_bf16_f32 v56, v33, v52
	v_lshlrev_b32_e32 v33, 16, v103
	v_lshlrev_b32_e32 v52, 16, v229
	v_mul_f32_e32 v33, v52, v33
	v_and_b32_e32 v52, 0xffff0000, v229
	v_and_b32_e32 v53, 0xffff0000, v103
	v_mul_f32_e32 v52, v52, v53
	v_cvt_pk_bf16_f32 v57, v33, v52
	v_add_co_u32_e32 v52, vcc, s66, v46
	s_nop 1
	v_addc_co_u32_e32 v53, vcc, 0, v47, vcc
	global_store_dwordx4 v[52:53], v[54:57], off
	s_waitcnt lgkmcnt(0)
	s_nop 0
	v_mul_f32_e32 v16, v16, v230
	v_cvt_pk_bf16_f32 v16, v16, v32
	v_mul_f32_e32 v0, v0, v230
	ds_write_b16 v84, v16
	v_cvt_pk_bf16_f32 v0, v0, v32
	ds_write_b16 v84, v0 offset:64
	v_mov_b32_e32 v33, v32
	s_nop 0
	v_mul_f32_e32 v0, v17, v231
	v_cvt_pk_bf16_f32 v0, v0, v32
	ds_write_b16 v64, v0
	v_mul_f32_e32 v0, v1, v231
	v_cvt_pk_bf16_f32 v0, v0, v32
	ds_write_b16 v64, v0 offset:64
	s_nop 0
	v_mul_f32_e32 v0, v18, v232
	v_cvt_pk_bf16_f32 v0, v0, v32
	ds_write_b16 v65, v0
	v_mul_f32_e32 v0, v2, v232
	v_cvt_pk_bf16_f32 v0, v0, v32
	ds_write_b16 v65, v0 offset:64
	s_nop 0
	v_mul_f32_e32 v0, v19, v233
	v_cvt_pk_bf16_f32 v0, v0, v32
	ds_write_b16 v66, v0
	v_mul_f32_e32 v0, v3, v233
	v_cvt_pk_bf16_f32 v0, v0, v32
	ds_write_b16 v66, v0 offset:64
	s_nop 0
	v_mul_f32_e32 v0, v20, v234
	v_cvt_pk_bf16_f32 v0, v0, v32
	ds_write_b16 v67, v0
	v_mul_f32_e32 v0, v4, v234
	v_cvt_pk_bf16_f32 v0, v0, v32
	ds_write_b16 v67, v0 offset:64
	v_lshlrev_b32_e32 v4, 16, v80
	s_nop 0
	v_mul_f32_e32 v0, v21, v235
	v_cvt_pk_bf16_f32 v0, v0, v32
	ds_write_b16 v68, v0
	v_mul_f32_e32 v0, v5, v235
	v_cvt_pk_bf16_f32 v0, v0, v32
	ds_write_b16 v68, v0 offset:64
	s_nop 0
	v_mul_f32_e32 v0, v22, v236
	v_cvt_pk_bf16_f32 v0, v0, v32
	ds_write_b16 v69, v0
	v_mul_f32_e32 v0, v6, v236
	v_cvt_pk_bf16_f32 v0, v0, v32
	ds_write_b16 v69, v0 offset:64
	s_nop 0
	v_mul_f32_e32 v0, v23, v237
	v_cvt_pk_bf16_f32 v0, v0, v32
	ds_write_b16 v70, v0
	v_mul_f32_e32 v0, v7, v237
	v_cvt_pk_bf16_f32 v0, v0, v32
	ds_write_b16 v70, v0 offset:64
	s_nop 0
	v_mul_f32_e32 v0, v24, v238
	v_cvt_pk_bf16_f32 v0, v0, v32
	ds_write_b16 v71, v0
	v_mul_f32_e32 v0, v8, v238
	v_cvt_pk_bf16_f32 v0, v0, v32
	ds_write_b16 v71, v0 offset:64
	s_nop 0
	v_mul_f32_e32 v0, v25, v239
	v_cvt_pk_bf16_f32 v0, v0, v32
	ds_write_b16 v72, v0
	v_mul_f32_e32 v0, v9, v239
	v_cvt_pk_bf16_f32 v0, v0, v32
	ds_write_b16 v72, v0 offset:64
	s_nop 0
	v_mul_f32_e32 v0, v26, v240
	v_cvt_pk_bf16_f32 v0, v0, v32
	ds_write_b16 v73, v0
	v_mul_f32_e32 v0, v10, v240
	v_cvt_pk_bf16_f32 v0, v0, v32
	ds_write_b16 v73, v0 offset:64
	s_nop 0
	v_mul_f32_e32 v0, v27, v241
	v_cvt_pk_bf16_f32 v0, v0, v32
	ds_write_b16 v74, v0
	v_mul_f32_e32 v0, v11, v241
	v_cvt_pk_bf16_f32 v0, v0, v32
	ds_write_b16 v74, v0 offset:64
	s_nop 0
	v_mul_f32_e32 v0, v28, v242
	v_cvt_pk_bf16_f32 v0, v0, v32
	ds_write_b16 v75, v0
	v_mul_f32_e32 v0, v12, v242
	v_cvt_pk_bf16_f32 v0, v0, v32
	ds_write_b16 v75, v0 offset:64
	s_nop 0
	v_mul_f32_e32 v0, v29, v243
	v_cvt_pk_bf16_f32 v0, v0, v32
	ds_write_b16 v60, v0
	v_mul_f32_e32 v0, v13, v243
	v_cvt_pk_bf16_f32 v0, v0, v32
	ds_write_b16 v60, v0 offset:64
	s_nop 0
	v_mul_f32_e32 v0, v30, v244
	v_cvt_pk_bf16_f32 v0, v0, v32
	ds_write_b16 v61, v0
	v_mul_f32_e32 v0, v14, v244
	v_cvt_pk_bf16_f32 v0, v0, v32
	ds_write_b16 v61, v0 offset:64
	s_nop 0
	v_mul_f32_e32 v0, v31, v245
	v_cvt_pk_bf16_f32 v0, v0, v32
	ds_write_b16 v76, v0
	v_mul_f32_e32 v0, v15, v245
	v_cvt_pk_bf16_f32 v0, v0, v32
	ds_write_b16 v76, v0 offset:64
	s_waitcnt lgkmcnt(0)
	ds_read_b128 v[214:217], v77
	ds_read_b128 v[218:221], v77 offset:1024
	ds_read_b128 v[222:225], v77 offset:2048
	ds_read_b128 v[226:229], v77 offset:3072
	s_waitcnt lgkmcnt(0)
; __device__ __forceinline__ void attn_phase(const bf16_t* __restrict__ Q, const bf16_t* __restrict__ KN, const bf16_t* __restrict__ KR, const bf16_t* __restrict__ V, ...
;     ...
;         m_reg = -1e30f; l_reg = 0;
; #pragma unroll
;         for (int d = 0; d < 4; ++d) o[d] = f32x16{};
	v_lshlrev_b32_e32 v5, 16, v214
	v_mul_f32_e32 v4, v5, v4
	v_and_b32_e32 v0, 0xffff0000, v214
	v_and_b32_e32 v5, 0xffff0000, v80
	v_mul_f32_e32 v0, v0, v5
	v_cvt_pk_bf16_f32 v0, v4, v0
	v_lshlrev_b32_e32 v4, 16, v81
	v_lshlrev_b32_e32 v5, 16, v215
	v_mul_f32_e32 v4, v5, v4
	v_and_b32_e32 v1, 0xffff0000, v215
	v_and_b32_e32 v5, 0xffff0000, v81
	v_mul_f32_e32 v1, v1, v5
	v_cvt_pk_bf16_f32 v1, v4, v1
	v_lshlrev_b32_e32 v4, 16, v82
	v_lshlrev_b32_e32 v5, 16, v216
	v_mul_f32_e32 v4, v5, v4
	v_and_b32_e32 v2, 0xffff0000, v216
	v_and_b32_e32 v5, 0xffff0000, v82
	v_mul_f32_e32 v2, v2, v5
	v_cvt_pk_bf16_f32 v2, v4, v2
	v_lshlrev_b32_e32 v4, 16, v83
	v_lshlrev_b32_e32 v5, 16, v217
	v_mul_f32_e32 v4, v5, v4
	v_and_b32_e32 v3, 0xffff0000, v217
	v_and_b32_e32 v5, 0xffff0000, v83
	v_mul_f32_e32 v3, v3, v5
	v_cvt_pk_bf16_f32 v3, v4, v3
	global_store_dwordx4 v[46:47], v[0:3], off offset:128
	v_mov_b32_e32 v46, v32
	v_mov_b32_e32 v47, v32
	v_lshlrev_b32_e32 v0, 16, v42
	s_waitcnt lgkmcnt(0)
	v_lshlrev_b32_e32 v1, 16, v218
	v_mul_f32_e32 v0, v1, v0
	v_and_b32_e32 v1, 0xffff0000, v218
	v_and_b32_e32 v2, 0xffff0000, v42
	v_mul_f32_e32 v1, v1, v2
	v_cvt_pk_bf16_f32 v0, v0, v1
	v_lshlrev_b32_e32 v1, 16, v43
	v_lshlrev_b32_e32 v2, 16, v219
	v_mul_f32_e32 v1, v2, v1
	v_and_b32_e32 v2, 0xffff0000, v219
	v_and_b32_e32 v3, 0xffff0000, v43
	v_mul_f32_e32 v2, v2, v3
	v_cvt_pk_bf16_f32 v1, v1, v2
	v_lshlrev_b32_e32 v2, 16, v44
	v_lshlrev_b32_e32 v3, 16, v220
	v_mul_f32_e32 v2, v3, v2
	v_and_b32_e32 v3, 0xffff0000, v220
	v_and_b32_e32 v4, 0xffff0000, v44
	v_mul_f32_e32 v3, v3, v4
	v_cvt_pk_bf16_f32 v2, v2, v3
	v_lshlrev_b32_e32 v3, 16, v45
	v_lshlrev_b32_e32 v4, 16, v221
	v_mul_f32_e32 v3, v4, v3
	v_and_b32_e32 v4, 0xffff0000, v221
	v_and_b32_e32 v5, 0xffff0000, v45
	v_mul_f32_e32 v4, v4, v5
	v_cvt_pk_bf16_f32 v3, v3, v4
	global_store_dwordx4 v[48:49], v[0:3], off offset:128
	v_mov_b32_e32 v42, v32
	v_mov_b32_e32 v43, v32
	v_lshlrev_b32_e32 v0, 16, v38
	s_waitcnt lgkmcnt(0)
	v_lshlrev_b32_e32 v1, 16, v222
	v_mul_f32_e32 v0, v1, v0
	v_and_b32_e32 v1, 0xffff0000, v222
	v_and_b32_e32 v2, 0xffff0000, v38
	v_mul_f32_e32 v1, v1, v2
	v_cvt_pk_bf16_f32 v0, v0, v1
	v_lshlrev_b32_e32 v1, 16, v39
	v_lshlrev_b32_e32 v2, 16, v223
	v_mul_f32_e32 v1, v2, v1
	v_and_b32_e32 v2, 0xffff0000, v223
	v_and_b32_e32 v3, 0xffff0000, v39
	v_mul_f32_e32 v2, v2, v3
	v_cvt_pk_bf16_f32 v1, v1, v2
	v_lshlrev_b32_e32 v2, 16, v40
	v_lshlrev_b32_e32 v3, 16, v224
	v_mul_f32_e32 v2, v3, v2
	v_and_b32_e32 v3, 0xffff0000, v224
	v_and_b32_e32 v4, 0xffff0000, v40
	v_mul_f32_e32 v3, v3, v4
	v_cvt_pk_bf16_f32 v2, v2, v3
	v_lshlrev_b32_e32 v3, 16, v41
	v_lshlrev_b32_e32 v4, 16, v225
	v_mul_f32_e32 v3, v4, v3
	v_and_b32_e32 v4, 0xffff0000, v225
	v_and_b32_e32 v5, 0xffff0000, v41
	v_mul_f32_e32 v4, v4, v5
	v_cvt_pk_bf16_f32 v3, v3, v4
	global_store_dwordx4 v[50:51], v[0:3], off offset:128
	v_mov_b32_e32 v38, v32
	v_mov_b32_e32 v39, v32
	s_waitcnt vmcnt(7)
	v_lshlrev_b32_e32 v0, 16, v34
	s_waitcnt lgkmcnt(0)
	v_lshlrev_b32_e32 v1, 16, v226
	v_mul_f32_e32 v0, v1, v0
	v_and_b32_e32 v1, 0xffff0000, v226
	v_and_b32_e32 v2, 0xffff0000, v34
	v_mul_f32_e32 v1, v1, v2
	v_cvt_pk_bf16_f32 v0, v0, v1
	v_lshlrev_b32_e32 v1, 16, v35
	v_lshlrev_b32_e32 v2, 16, v227
	v_mul_f32_e32 v1, v2, v1
	v_and_b32_e32 v2, 0xffff0000, v227
	v_and_b32_e32 v3, 0xffff0000, v35
	v_mul_f32_e32 v2, v2, v3
	v_cvt_pk_bf16_f32 v1, v1, v2
	v_lshlrev_b32_e32 v2, 16, v36
	v_lshlrev_b32_e32 v3, 16, v228
	v_mul_f32_e32 v2, v3, v2
	v_and_b32_e32 v3, 0xffff0000, v228
	v_and_b32_e32 v4, 0xffff0000, v36
	v_mul_f32_e32 v3, v3, v4
	v_cvt_pk_bf16_f32 v2, v2, v3
	v_lshlrev_b32_e32 v3, 16, v37
	v_lshlrev_b32_e32 v4, 16, v229
	v_mul_f32_e32 v3, v4, v3
	v_and_b32_e32 v4, 0xffff0000, v229
	v_and_b32_e32 v5, 0xffff0000, v37
	v_mul_f32_e32 v4, v4, v5
	v_cvt_pk_bf16_f32 v3, v3, v4
	global_store_dwordx4 v[52:53], v[0:3], off offset:128
	s_waitcnt lgkmcnt(0)
	v_mov_b32_e32 v34, v32
	v_mov_b32_e32 v35, v32
	v_mov_b32_e32 v36, v32
	v_mov_b32_e32 v37, v32
	v_mov_b32_e32 v40, v32
	v_mov_b32_e32 v41, v32
	v_mov_b32_e32 v44, v32
	v_mov_b32_e32 v45, v32
	v_mov_b64_e32 v[78:79], v[46:47]
	v_mov_b64_e32 v[62:63], v[46:47]
	v_mov_b64_e32 v[16:17], v[32:33]
	v_mov_b64_e32 v[0:1], v[32:33]
	v_mov_b64_e32 v[76:77], v[44:45]
	v_mov_b64_e32 v[74:75], v[42:43]
	v_mov_b64_e32 v[72:73], v[40:41]
	v_mov_b64_e32 v[70:71], v[38:39]
	v_mov_b64_e32 v[68:69], v[36:37]
	v_mov_b64_e32 v[66:67], v[34:35]
	v_mov_b64_e32 v[64:65], v[32:33]
	v_mov_b64_e32 v[60:61], v[44:45]
	v_mov_b64_e32 v[58:59], v[42:43]
	v_mov_b64_e32 v[56:57], v[40:41]
	v_mov_b64_e32 v[54:55], v[38:39]
	v_mov_b64_e32 v[52:53], v[36:37]
	v_mov_b64_e32 v[50:51], v[34:35]
	v_mov_b64_e32 v[48:49], v[32:33]
	v_mov_b64_e32 v[18:19], v[34:35]
	v_mov_b64_e32 v[20:21], v[36:37]
	v_mov_b64_e32 v[22:23], v[38:39]
	v_mov_b64_e32 v[24:25], v[40:41]
	v_mov_b64_e32 v[26:27], v[42:43]
	v_mov_b64_e32 v[28:29], v[44:45]
	v_mov_b64_e32 v[30:31], v[46:47]
	v_mov_b64_e32 v[2:3], v[34:35]
	v_mov_b64_e32 v[4:5], v[36:37]
	v_mov_b64_e32 v[6:7], v[38:39]
	v_mov_b64_e32 v[8:9], v[40:41]
	v_mov_b64_e32 v[10:11], v[42:43]
	v_mov_b64_e32 v[12:13], v[44:45]
	v_mov_b64_e32 v[14:15], v[46:47]

; #define SBAR() __builtin_amdgcn_sched_barrier(0)
; __device__ __forceinline__ void pv_d0(f32x16* o, int vb, bf16x8 pa0, bf16x8 pa1, bf16x8 pa2, bf16x8 pa3) {
;   VFrag fa, fb;
;   v_read8<0>(fa, vb); v_read8<1>(fb, vb);
;   asm volatile("s_waitcnt lgkmcnt(8)" ::: "memory"); SBAR(); pv_mma(o[0], fa, pa0, pa1, pa2, pa3); SBAR();
;   v_read8<2>(fa, vb);
;   asm volatile("s_waitcnt lgkmcnt(8)" ::: "memory"); SBAR(); pv_mma(o[1], fb, pa0, pa1, pa2, pa3); SBAR();
;   v_read8<3>(fb, vb);
;   asm volatile("s_waitcnt lgkmcnt(8)" ::: "memory"); SBAR(); pv_mma(o[2], fa, pa0, pa1, pa2, pa3); SBAR();
;   asm volatile("s_waitcnt lgkmcnt(0)" ::: "memory"); SBAR(); pv_mma(o[3], fb, pa0, pa1, pa2, pa3); SBAR();
; }
.LBB0_1158:
	s_add_i32 s3, s47, -1
	s_mul_i32 s3, s3, s63
	s_add_i32 s3, s3, s46
	s_lshl_b32 s6, s3, 4
	s_lshl_b32 s3, s3, 8
	s_and_b32 s7, s6, 0xfffff800
	s_and_b32 s3, s3, 0x700
	s_or_b32 s3, s7, s3
	v_add_u32_e32 v32, s3, v210
	v_ashrrev_i32_e32 v33, 31, v32
	s_waitcnt vmcnt(0)
	v_lshlrev_b64 v[112:113], 11, v[32:33]
	s_and_b32 s3, s6, 0x780
	v_or_b32_e32 v32, s3, v112
	v_or_b32_e32 v112, v32, v184
	v_lshl_add_u64 v[32:33], v[112:113], 1, s[14:15]
	s_mov_b32 s9, 0x8000
	v_add_co_u32_e32 v34, vcc, s9, v32
	s_mov_b32 s8, 0x10000
	s_nop 0
	v_addc_co_u32_e32 v35, vcc, 0, v33, vcc
	v_add_co_u32_e32 v36, vcc, s8, v32
	s_mov_b32 s3, 0x18000
	s_nop 0
	v_addc_co_u32_e32 v37, vcc, 0, v33, vcc
	v_add_co_u32_e32 v114, vcc, s3, v32
	v_lshl_add_u32 v146, s72, 14, v209
	s_nop 0
	v_addc_co_u32_e32 v115, vcc, 0, v33, vcc
	global_load_dwordx4 v[108:111], v[32:33], off
	global_load_dwordx4 v[44:47], v[32:33], off offset:128
	global_load_dwordx4 v[104:107], v[34:35], off
	global_load_dwordx4 v[40:43], v[34:35], off offset:128
	global_load_dwordx4 v[100:103], v[36:37], off
	s_nop 0
	global_load_dwordx4 v[36:39], v[36:37], off offset:128
	s_nop 0
	global_load_dwordx4 v[80:83], v[114:115], off
	global_load_dwordx4 v[32:35], v[114:115], off offset:128
	ds_read_b64_tr_b16 v[114:115], v146 offset:0
	ds_read_b64_tr_b16 v[116:117], v146 offset:0x800
	ds_read_b64_tr_b16 v[118:119], v146 offset:0x1000
	ds_read_b64_tr_b16 v[120:121], v146 offset:0x1800
	ds_read_b64_tr_b16 v[122:123], v146 offset:0x2000
	ds_read_b64_tr_b16 v[124:125], v146 offset:0x2800
	ds_read_b64_tr_b16 v[126:127], v146 offset:0x3000
	ds_read_b64_tr_b16 v[128:129], v146 offset:0x3800
	ds_read_b64_tr_b16 v[130:131], v146 offset:0x200
	ds_read_b64_tr_b16 v[132:133], v146 offset:0xa00
	ds_read_b64_tr_b16 v[134:135], v146 offset:0x1200
	ds_read_b64_tr_b16 v[136:137], v146 offset:0x1a00
	ds_read_b64_tr_b16 v[138:139], v146 offset:0x2200
	ds_read_b64_tr_b16 v[140:141], v146 offset:0x2a00
	ds_read_b64_tr_b16 v[142:143], v146 offset:0x3200
	ds_read_b64_tr_b16 v[144:145], v146 offset:0x3a00
	s_waitcnt lgkmcnt(8)
	s_nop 0
	v_mfma_f32_32x32x16_bf16 v[64:79], v[96:99], v[114:117], v[64:79]
	v_mfma_f32_32x32x16_bf16 v[64:79], v[92:95], v[118:121], v[64:79]
	v_mfma_f32_32x32x16_bf16 v[64:79], v[88:91], v[122:125], v[64:79]
	v_mfma_f32_32x32x16_bf16 v[64:79], v[84:87], v[126:129], v[64:79]
	ds_read_b64_tr_b16 v[114:115], v146 offset:0x400
	ds_read_b64_tr_b16 v[116:117], v146 offset:0xc00
	ds_read_b64_tr_b16 v[118:119], v146 offset:0x1400
	ds_read_b64_tr_b16 v[120:121], v146 offset:0x1c00
	ds_read_b64_tr_b16 v[122:123], v146 offset:0x2400
	ds_read_b64_tr_b16 v[124:125], v146 offset:0x2c00
	ds_read_b64_tr_b16 v[126:127], v146 offset:0x3400
	ds_read_b64_tr_b16 v[128:129], v146 offset:0x3c00
	s_waitcnt lgkmcnt(8)
	v_mfma_f32_32x32x16_bf16 v[48:63], v[96:99], v[130:133], v[48:63]
	v_mfma_f32_32x32x16_bf16 v[48:63], v[92:95], v[134:137], v[48:63]
	v_mfma_f32_32x32x16_bf16 v[48:63], v[88:91], v[138:141], v[48:63]
	v_mfma_f32_32x32x16_bf16 v[48:63], v[84:87], v[142:145], v[48:63]
	ds_read_b64_tr_b16 v[130:131], v146 offset:0x600
	ds_read_b64_tr_b16 v[132:133], v146 offset:0xe00
	ds_read_b64_tr_b16 v[134:135], v146 offset:0x1600
	ds_read_b64_tr_b16 v[136:137], v146 offset:0x1e00
	ds_read_b64_tr_b16 v[138:139], v146 offset:0x2600
	ds_read_b64_tr_b16 v[140:141], v146 offset:0x2e00
	ds_read_b64_tr_b16 v[142:143], v146 offset:0x3600
	ds_read_b64_tr_b16 v[144:145], v146 offset:0x3e00
	s_waitcnt lgkmcnt(8)
	v_mfma_f32_32x32x16_bf16 v[16:31], v[96:99], v[114:117], v[16:31]
	v_mfma_f32_32x32x16_bf16 v[16:31], v[92:95], v[118:121], v[16:31]
	v_mfma_f32_32x32x16_bf16 v[16:31], v[88:91], v[122:125], v[16:31]
	v_mfma_f32_32x32x16_bf16 v[16:31], v[84:87], v[126:129], v[16:31]
	s_waitcnt lgkmcnt(0)
	v_mfma_f32_32x32x16_bf16 v[0:15], v[96:99], v[130:133], v[0:15]
	v_mfma_f32_32x32x16_bf16 v[0:15], v[92:95], v[134:137], v[0:15]
	v_mfma_f32_32x32x16_bf16 v[0:15], v[88:91], v[138:141], v[0:15]
	v_mfma_f32_32x32x16_bf16 v[0:15], v[84:87], v[142:145], v[0:15]
	s_and_saveexec_b64 s[6:7], s[0:1]
	ds_write_b32 v208, v187
	s_or_b64 exec, exec, s[6:7]
	s_waitcnt lgkmcnt(0)
	ds_read_b32 v230, v185
	ds_read_b32 v231, v185 offset:4
	ds_read_b32 v232, v185 offset:8
	ds_read_b32 v233, v185 offset:12
	ds_read_b32 v234, v185 offset:32
	ds_read_b32 v235, v185 offset:36
	ds_read_b32 v236, v185 offset:40
	ds_read_b32 v237, v185 offset:44
	ds_read_b32 v238, v185 offset:64
	ds_read_b32 v239, v185 offset:68
	ds_read_b32 v240, v185 offset:72
	ds_read_b32 v241, v185 offset:76
	ds_read_b32 v242, v185 offset:96
	ds_read_b32 v243, v185 offset:100
	ds_read_b32 v244, v185 offset:104
	ds_read_b32 v245, v185 offset:108
	s_waitcnt lgkmcnt(0)
	v_rcp_f32_e32 v230, v230
	v_rcp_f32_e32 v231, v231
	v_rcp_f32_e32 v232, v232
	v_rcp_f32_e32 v233, v233
	v_rcp_f32_e32 v234, v234
	v_rcp_f32_e32 v235, v235
	v_rcp_f32_e32 v236, v236
	v_rcp_f32_e32 v237, v237
	v_rcp_f32_e32 v238, v238
	v_rcp_f32_e32 v239, v239
	v_rcp_f32_e32 v240, v240
	v_rcp_f32_e32 v241, v241
	v_rcp_f32_e32 v242, v242
	v_rcp_f32_e32 v243, v243
	v_rcp_f32_e32 v244, v244
	v_rcp_f32_e32 v245, v245
	s_nop 0
	v_add_u32_e32 v86, v190, v207
	v_add_u32_e32 v87, v188, v189
	v_readlane_b32 s68, v247, 34
	v_readlane_b32 s82, v247, 48
	v_mov_b32_e32 v84, 0
	v_readlane_b32 s83, v247, 49
	v_readlane_b32 s69, v247, 35
	v_mul_f32_e32 v64, v64, v230
	v_mul_f32_e32 v48, v48, v230
	v_cvt_pk_bf16_f32 v64, v64, v84
	ds_write_b16 v86, v64
	v_cvt_pk_bf16_f32 v48, v48, v84
	ds_write_b16 v86, v48 offset:64
	v_add_u32_e32 v85, v190, v206
	v_readlane_b32 s70, v247, 36
	v_readlane_b32 s71, v247, 37
	v_readlane_b32 s72, v247, 38
	v_readlane_b32 s73, v247, 39
	v_readlane_b32 s74, v247, 40
	v_mul_f32_e32 v48, v65, v231
	v_mul_f32_e32 v49, v49, v231
	v_cvt_pk_bf16_f32 v48, v48, v84
	ds_write_b16 v85, v48
	v_cvt_pk_bf16_f32 v48, v49, v84
	ds_write_b16 v85, v48 offset:64
	v_add_u32_e32 v64, v190, v205
	v_add_u32_e32 v65, v190, v204
	v_readlane_b32 s75, v247, 41
	v_readlane_b32 s76, v247, 42
	v_readlane_b32 s77, v247, 43
	v_readlane_b32 s78, v247, 44
	v_mul_f32_e32 v48, v66, v232
	v_mul_f32_e32 v49, v50, v232
	v_cvt_pk_bf16_f32 v48, v48, v84
	ds_write_b16 v64, v48
	v_cvt_pk_bf16_f32 v48, v49, v84
	ds_write_b16 v64, v48 offset:64
	v_add_u32_e32 v66, v190, v203
	v_readlane_b32 s79, v247, 45
	v_readlane_b32 s80, v247, 46
	v_readlane_b32 s81, v247, 47
	v_mul_f32_e32 v48, v67, v233
	v_mul_f32_e32 v49, v51, v233
	v_cvt_pk_bf16_f32 v48, v48, v84
	ds_write_b16 v65, v48
	v_cvt_pk_bf16_f32 v48, v49, v84
	ds_write_b16 v65, v48 offset:64
	v_add_u32_e32 v67, v190, v202
	s_nop 0
	v_mul_f32_e32 v48, v68, v234
	v_mul_f32_e32 v49, v52, v234
	v_cvt_pk_bf16_f32 v48, v48, v84
	ds_write_b16 v66, v48
	v_cvt_pk_bf16_f32 v48, v49, v84
	ds_write_b16 v66, v48 offset:64
	v_add_u32_e32 v68, v190, v201
	s_nop 0
	v_mul_f32_e32 v48, v69, v235
	v_mul_f32_e32 v49, v53, v235
	v_cvt_pk_bf16_f32 v48, v48, v84
	ds_write_b16 v67, v48
	v_cvt_pk_bf16_f32 v48, v49, v84
	ds_write_b16 v67, v48 offset:64
	v_add_u32_e32 v69, v190, v200
	s_nop 0
	v_mul_f32_e32 v48, v70, v236
	v_mul_f32_e32 v49, v54, v236
	v_cvt_pk_bf16_f32 v48, v48, v84
	ds_write_b16 v68, v48
	v_cvt_pk_bf16_f32 v48, v49, v84
	ds_write_b16 v68, v48 offset:64
	v_add_u32_e32 v70, v190, v199
	s_waitcnt vmcnt(7)
	v_lshlrev_b32_e32 v54, 16, v108
	s_nop 0
	v_mul_f32_e32 v48, v71, v237
	v_mul_f32_e32 v49, v55, v237
	v_cvt_pk_bf16_f32 v48, v48, v84
	ds_write_b16 v69, v48
	v_cvt_pk_bf16_f32 v48, v49, v84
	ds_write_b16 v69, v48 offset:64
	v_add_u32_e32 v71, v190, v197
	v_and_b32_e32 v55, 0xffff0000, v108
	s_nop 0
	v_mul_f32_e32 v48, v72, v238
	v_mul_f32_e32 v49, v56, v238
	v_cvt_pk_bf16_f32 v48, v48, v84
	ds_write_b16 v70, v48
	v_cvt_pk_bf16_f32 v48, v49, v84
	ds_write_b16 v70, v48 offset:64
	v_add_u32_e32 v72, v190, v196
	v_lshlrev_b32_e32 v56, 16, v109
	s_nop 0
	v_mul_f32_e32 v48, v73, v239
	v_mul_f32_e32 v49, v57, v239
	v_cvt_pk_bf16_f32 v48, v48, v84
	ds_write_b16 v71, v48
	v_cvt_pk_bf16_f32 v48, v49, v84
	ds_write_b16 v71, v48 offset:64
	v_add_u32_e32 v73, v190, v195
	v_and_b32_e32 v57, 0xffff0000, v109
	s_nop 0
	v_mul_f32_e32 v48, v74, v240
	v_mul_f32_e32 v49, v58, v240
	v_cvt_pk_bf16_f32 v48, v48, v84
	ds_write_b16 v72, v48
	v_cvt_pk_bf16_f32 v48, v49, v84
	ds_write_b16 v72, v48 offset:64
	v_add_u32_e32 v74, v190, v194
	v_lshlrev_b32_e32 v58, 16, v110
	s_nop 0
	v_mul_f32_e32 v48, v75, v241
	v_mul_f32_e32 v49, v59, v241
	v_cvt_pk_bf16_f32 v48, v48, v84
	ds_write_b16 v73, v48
	v_cvt_pk_bf16_f32 v48, v49, v84
	ds_write_b16 v73, v48 offset:64
	v_add_u32_e32 v75, v190, v193
	v_and_b32_e32 v59, 0xffff0000, v110
	s_nop 0
	v_mul_f32_e32 v48, v76, v242
	v_mul_f32_e32 v49, v60, v242
	v_cvt_pk_bf16_f32 v48, v48, v84
	ds_write_b16 v74, v48
	v_cvt_pk_bf16_f32 v48, v49, v84
	ds_write_b16 v74, v48 offset:64
	v_add_u32_e32 v76, v190, v192
	v_lshlrev_b32_e32 v60, 16, v111
	s_nop 0
	v_mul_f32_e32 v48, v77, v243
	v_mul_f32_e32 v49, v61, v243
	v_cvt_pk_bf16_f32 v48, v48, v84
	ds_write_b16 v75, v48
	v_cvt_pk_bf16_f32 v50, v49, v84
	ds_write_b16 v75, v50 offset:64
	v_add_u32_e32 v77, v190, v191
	v_and_b32_e32 v61, 0xffff0000, v111
	v_lshl_add_u64 v[48:49], v[112:113], 1, s[18:19]
	s_nop 0
	v_mul_f32_e32 v50, v78, v244
	v_mul_f32_e32 v51, v62, v244
	v_cvt_pk_bf16_f32 v50, v50, v84
	ds_write_b16 v76, v50
	v_cvt_pk_bf16_f32 v50, v51, v84
	ds_write_b16 v76, v50 offset:64
	s_waitcnt vmcnt(5)
	v_lshlrev_b32_e32 v62, 16, v104
	s_nop 0
	v_mul_f32_e32 v50, v79, v245
	v_cvt_pk_bf16_f32 v50, v50, v84
	v_mul_f32_e32 v51, v63, v245
	ds_write_b16 v77, v50
	v_cvt_pk_bf16_f32 v50, v51, v84
	ds_write_b16 v77, v50 offset:64
	s_waitcnt lgkmcnt(0)
	ds_read_b128 v[214:217], v87
	ds_read_b128 v[218:221], v87 offset:1024
	ds_read_b128 v[222:225], v87 offset:2048
	ds_read_b128 v[226:229], v87 offset:3072
	v_and_b32_e32 v63, 0xffff0000, v104
	s_waitcnt lgkmcnt(0)
	v_lshlrev_b32_e32 v78, 16, v214
	v_and_b32_e32 v50, 0xffff0000, v214
	v_lshlrev_b32_e32 v79, 16, v215
	v_and_b32_e32 v51, 0xffff0000, v215
	v_lshlrev_b32_e32 v88, 16, v216
	v_and_b32_e32 v52, 0xffff0000, v216
	v_lshlrev_b32_e32 v89, 16, v217
	v_and_b32_e32 v53, 0xffff0000, v217
	v_mul_f32_e32 v54, v78, v54
	v_mul_f32_e32 v50, v50, v55
	v_mul_f32_e32 v55, v79, v56
	v_mul_f32_e32 v51, v51, v57
	v_mul_f32_e32 v56, v88, v58
	v_mul_f32_e32 v52, v52, v59
	v_mul_f32_e32 v57, v89, v60
	v_mul_f32_e32 v53, v53, v61
	v_cvt_pk_bf16_f32 v50, v54, v50
	v_cvt_pk_bf16_f32 v51, v55, v51
	v_cvt_pk_bf16_f32 v52, v56, v52
	v_cvt_pk_bf16_f32 v53, v57, v53
	v_lshlrev_b32_e32 v58, 16, v105
	v_and_b32_e32 v59, 0xffff0000, v105
	global_store_dwordx4 v[48:49], v[50:53], off
	v_lshlrev_b32_e32 v60, 16, v106
	s_waitcnt lgkmcnt(0)
	v_lshlrev_b32_e32 v50, 16, v218
	v_and_b32_e32 v51, 0xffff0000, v218
	v_lshlrev_b32_e32 v52, 16, v219
	v_and_b32_e32 v53, 0xffff0000, v219
	v_mul_f32_e32 v50, v50, v62
	v_mul_f32_e32 v51, v51, v63
	v_mul_f32_e32 v54, v52, v58
	v_mul_f32_e32 v53, v53, v59
	v_cvt_pk_bf16_f32 v52, v50, v51
	v_cvt_pk_bf16_f32 v53, v54, v53
	v_lshlrev_b32_e32 v50, 16, v220
	v_and_b32_e32 v51, 0xffff0000, v220
	v_and_b32_e32 v54, 0xffff0000, v106
	v_mul_f32_e32 v50, v50, v60
	v_mul_f32_e32 v51, v51, v54
	v_cvt_pk_bf16_f32 v54, v50, v51
	v_lshlrev_b32_e32 v50, 16, v107
	v_lshlrev_b32_e32 v51, 16, v221
	v_mul_f32_e32 v50, v51, v50
	v_and_b32_e32 v51, 0xffff0000, v221
	v_and_b32_e32 v55, 0xffff0000, v107
	v_mul_f32_e32 v51, v51, v55
	v_cvt_pk_bf16_f32 v55, v50, v51
	v_add_co_u32_e32 v50, vcc, s9, v48
	s_nop 1
	v_addc_co_u32_e32 v51, vcc, 0, v49, vcc
	global_store_dwordx4 v[50:51], v[52:55], off
	s_waitcnt vmcnt(5)
	s_nop 0
	v_lshlrev_b32_e32 v52, 16, v100
	s_waitcnt lgkmcnt(0)
	v_lshlrev_b32_e32 v53, 16, v222
	v_mul_f32_e32 v52, v53, v52
	v_and_b32_e32 v53, 0xffff0000, v222
	v_and_b32_e32 v54, 0xffff0000, v100
	v_mul_f32_e32 v53, v53, v54
	v_cvt_pk_bf16_f32 v54, v52, v53
	v_lshlrev_b32_e32 v52, 16, v101
	v_lshlrev_b32_e32 v53, 16, v223
	v_mul_f32_e32 v52, v53, v52
	v_and_b32_e32 v53, 0xffff0000, v223
	v_and_b32_e32 v55, 0xffff0000, v101
	v_mul_f32_e32 v53, v53, v55
	v_cvt_pk_bf16_f32 v55, v52, v53
	v_lshlrev_b32_e32 v52, 16, v102
	v_lshlrev_b32_e32 v53, 16, v224
	v_mul_f32_e32 v52, v53, v52
	v_and_b32_e32 v53, 0xffff0000, v224
	v_and_b32_e32 v56, 0xffff0000, v102
	v_mul_f32_e32 v53, v53, v56
	v_cvt_pk_bf16_f32 v56, v52, v53
	v_lshlrev_b32_e32 v52, 16, v103
	v_lshlrev_b32_e32 v53, 16, v225
	v_mul_f32_e32 v52, v53, v52
	v_and_b32_e32 v53, 0xffff0000, v225
	v_and_b32_e32 v57, 0xffff0000, v103
	v_mul_f32_e32 v53, v53, v57
	v_cvt_pk_bf16_f32 v57, v52, v53
	v_add_co_u32_e32 v52, vcc, s8, v48
	s_nop 1
	v_addc_co_u32_e32 v53, vcc, 0, v49, vcc
	global_store_dwordx4 v[52:53], v[54:57], off
	s_waitcnt vmcnt(4)
	s_nop 0
	v_lshlrev_b32_e32 v54, 16, v80
	s_waitcnt lgkmcnt(0)
	v_lshlrev_b32_e32 v55, 16, v226
	v_mul_f32_e32 v54, v55, v54
	v_and_b32_e32 v55, 0xffff0000, v226
	v_and_b32_e32 v56, 0xffff0000, v80
	v_mul_f32_e32 v55, v55, v56
	v_cvt_pk_bf16_f32 v56, v54, v55
	v_lshlrev_b32_e32 v54, 16, v81
	v_lshlrev_b32_e32 v55, 16, v227
	v_mul_f32_e32 v54, v55, v54
	v_and_b32_e32 v55, 0xffff0000, v227
	v_and_b32_e32 v57, 0xffff0000, v81
	v_mul_f32_e32 v55, v55, v57
	v_cvt_pk_bf16_f32 v57, v54, v55
	v_lshlrev_b32_e32 v54, 16, v82
	v_lshlrev_b32_e32 v55, 16, v228
	v_mul_f32_e32 v54, v55, v54
	v_and_b32_e32 v55, 0xffff0000, v228
	v_and_b32_e32 v58, 0xffff0000, v82
	v_mul_f32_e32 v55, v55, v58
	v_cvt_pk_bf16_f32 v58, v54, v55
	v_lshlrev_b32_e32 v54, 16, v83
	v_lshlrev_b32_e32 v55, 16, v229
	v_mul_f32_e32 v54, v55, v54
	v_and_b32_e32 v55, 0xffff0000, v229
	v_and_b32_e32 v59, 0xffff0000, v83
	v_mul_f32_e32 v55, v55, v59
	v_cvt_pk_bf16_f32 v59, v54, v55
	v_add_co_u32_e32 v54, vcc, s3, v48
	s_nop 1
	v_addc_co_u32_e32 v55, vcc, 0, v49, vcc
	global_store_dwordx4 v[54:55], v[56:59], off
	s_waitcnt lgkmcnt(0)
	s_and_b64 vcc, exec, s[4:5]
	s_nop 0
	v_mul_f32_e32 v16, v16, v230
	v_cvt_pk_bf16_f32 v16, v16, v84
	v_mul_f32_e32 v0, v0, v230
	ds_write_b16 v86, v16
	v_cvt_pk_bf16_f32 v0, v0, v84
	ds_write_b16 v86, v0 offset:64
	s_nop 0
	v_mul_f32_e32 v0, v17, v231
	v_cvt_pk_bf16_f32 v0, v0, v84
	ds_write_b16 v85, v0
	v_mul_f32_e32 v0, v1, v231
	v_cvt_pk_bf16_f32 v0, v0, v84
	ds_write_b16 v85, v0 offset:64
	s_nop 0
	v_mul_f32_e32 v0, v18, v232
	v_cvt_pk_bf16_f32 v0, v0, v84
	ds_write_b16 v64, v0
	v_mul_f32_e32 v0, v2, v232
	v_cvt_pk_bf16_f32 v0, v0, v84
	ds_write_b16 v64, v0 offset:64
	s_nop 0
	v_mul_f32_e32 v0, v19, v233
	v_cvt_pk_bf16_f32 v0, v0, v84
	ds_write_b16 v65, v0
	v_mul_f32_e32 v0, v3, v233
	v_cvt_pk_bf16_f32 v0, v0, v84
	ds_write_b16 v65, v0 offset:64
	s_nop 0
	v_mul_f32_e32 v0, v20, v234
	v_cvt_pk_bf16_f32 v0, v0, v84
	ds_write_b16 v66, v0
	v_mul_f32_e32 v0, v4, v234
	v_cvt_pk_bf16_f32 v0, v0, v84
	ds_write_b16 v66, v0 offset:64
	v_lshlrev_b32_e32 v4, 16, v44
	s_nop 0
	v_mul_f32_e32 v0, v21, v235
	v_cvt_pk_bf16_f32 v0, v0, v84
	ds_write_b16 v67, v0
	v_mul_f32_e32 v0, v5, v235
	v_cvt_pk_bf16_f32 v0, v0, v84
	ds_write_b16 v67, v0 offset:64
	s_nop 0
	v_mul_f32_e32 v0, v22, v236
	v_cvt_pk_bf16_f32 v0, v0, v84
	ds_write_b16 v68, v0
	v_mul_f32_e32 v0, v6, v236
	v_cvt_pk_bf16_f32 v0, v0, v84
	ds_write_b16 v68, v0 offset:64
	s_nop 0
	v_mul_f32_e32 v0, v23, v237
	v_cvt_pk_bf16_f32 v0, v0, v84
	ds_write_b16 v69, v0
	v_mul_f32_e32 v0, v7, v237
	v_cvt_pk_bf16_f32 v0, v0, v84
	ds_write_b16 v69, v0 offset:64
	s_nop 0
	v_mul_f32_e32 v0, v24, v238
	v_cvt_pk_bf16_f32 v0, v0, v84
	ds_write_b16 v70, v0
	v_mul_f32_e32 v0, v8, v238
	v_cvt_pk_bf16_f32 v0, v0, v84
	ds_write_b16 v70, v0 offset:64
	s_nop 0
	v_mul_f32_e32 v0, v25, v239
	v_cvt_pk_bf16_f32 v0, v0, v84
	ds_write_b16 v71, v0
	v_mul_f32_e32 v0, v9, v239
	v_cvt_pk_bf16_f32 v0, v0, v84
	ds_write_b16 v71, v0 offset:64
	s_nop 0
	v_mul_f32_e32 v0, v26, v240
	v_cvt_pk_bf16_f32 v0, v0, v84
	ds_write_b16 v72, v0
	v_mul_f32_e32 v0, v10, v240
	v_cvt_pk_bf16_f32 v0, v0, v84
	ds_write_b16 v72, v0 offset:64
	s_nop 0
	v_mul_f32_e32 v0, v27, v241
	v_cvt_pk_bf16_f32 v0, v0, v84
	ds_write_b16 v73, v0
	v_mul_f32_e32 v0, v11, v241
	v_cvt_pk_bf16_f32 v0, v0, v84
	ds_write_b16 v73, v0 offset:64
	s_nop 0
	v_mul_f32_e32 v0, v28, v242
	v_cvt_pk_bf16_f32 v0, v0, v84
	ds_write_b16 v74, v0
	v_mul_f32_e32 v0, v12, v242
	v_cvt_pk_bf16_f32 v0, v0, v84
	ds_write_b16 v74, v0 offset:64
	s_nop 0
	v_mul_f32_e32 v0, v29, v243
	v_cvt_pk_bf16_f32 v0, v0, v84
	ds_write_b16 v75, v0
	v_mul_f32_e32 v0, v13, v243
	v_cvt_pk_bf16_f32 v0, v0, v84
	ds_write_b16 v75, v0 offset:64
	s_nop 0
	v_mul_f32_e32 v0, v30, v244
	v_cvt_pk_bf16_f32 v0, v0, v84
	ds_write_b16 v76, v0
	v_mul_f32_e32 v0, v14, v244
	v_cvt_pk_bf16_f32 v0, v0, v84
	ds_write_b16 v76, v0 offset:64
	s_nop 0
	v_mul_f32_e32 v0, v31, v245
	v_cvt_pk_bf16_f32 v0, v0, v84
	ds_write_b16 v77, v0
	v_mul_f32_e32 v0, v15, v245
	v_cvt_pk_bf16_f32 v0, v0, v84
	ds_write_b16 v77, v0 offset:64
	s_waitcnt lgkmcnt(0)
	ds_read_b128 v[214:217], v87
	ds_read_b128 v[218:221], v87 offset:1024
	ds_read_b128 v[222:225], v87 offset:2048
	ds_read_b128 v[226:229], v87 offset:3072
	s_waitcnt lgkmcnt(0)
	v_lshlrev_b32_e32 v5, 16, v214
	v_mul_f32_e32 v4, v5, v4
	v_and_b32_e32 v0, 0xffff0000, v214
	v_and_b32_e32 v5, 0xffff0000, v44
	v_mul_f32_e32 v0, v0, v5
	v_cvt_pk_bf16_f32 v0, v4, v0
	v_lshlrev_b32_e32 v4, 16, v45
	v_lshlrev_b32_e32 v5, 16, v215
	v_mul_f32_e32 v4, v5, v4
	v_and_b32_e32 v1, 0xffff0000, v215
	v_and_b32_e32 v5, 0xffff0000, v45
	v_mul_f32_e32 v1, v1, v5
	v_cvt_pk_bf16_f32 v1, v4, v1
	v_lshlrev_b32_e32 v4, 16, v46
	v_lshlrev_b32_e32 v5, 16, v216
	v_mul_f32_e32 v4, v5, v4
	v_and_b32_e32 v2, 0xffff0000, v216
	v_and_b32_e32 v5, 0xffff0000, v46
	v_mul_f32_e32 v2, v2, v5
	v_cvt_pk_bf16_f32 v2, v4, v2
	v_lshlrev_b32_e32 v4, 16, v47
	v_lshlrev_b32_e32 v5, 16, v217
	v_mul_f32_e32 v4, v5, v4
	v_and_b32_e32 v3, 0xffff0000, v217
	v_and_b32_e32 v5, 0xffff0000, v47
	v_mul_f32_e32 v3, v3, v5
	v_cvt_pk_bf16_f32 v3, v4, v3
	global_store_dwordx4 v[48:49], v[0:3], off offset:128
	s_nop 1
	v_lshlrev_b32_e32 v0, 16, v40
	s_waitcnt lgkmcnt(0)
	v_lshlrev_b32_e32 v1, 16, v218
	v_mul_f32_e32 v0, v1, v0
	v_and_b32_e32 v1, 0xffff0000, v218
	v_and_b32_e32 v2, 0xffff0000, v40
	v_mul_f32_e32 v1, v1, v2
	v_cvt_pk_bf16_f32 v0, v0, v1
	v_lshlrev_b32_e32 v1, 16, v41
	v_lshlrev_b32_e32 v2, 16, v219
	v_mul_f32_e32 v1, v2, v1
	v_and_b32_e32 v2, 0xffff0000, v219
	v_and_b32_e32 v3, 0xffff0000, v41
	v_mul_f32_e32 v2, v2, v3
	v_cvt_pk_bf16_f32 v1, v1, v2
	v_lshlrev_b32_e32 v2, 16, v42
	v_lshlrev_b32_e32 v3, 16, v220
	v_mul_f32_e32 v2, v3, v2
	v_and_b32_e32 v3, 0xffff0000, v220
	v_and_b32_e32 v4, 0xffff0000, v42
	v_mul_f32_e32 v3, v3, v4
	v_cvt_pk_bf16_f32 v2, v2, v3
	v_lshlrev_b32_e32 v3, 16, v43
	v_lshlrev_b32_e32 v4, 16, v221
	v_mul_f32_e32 v3, v4, v3
	v_and_b32_e32 v4, 0xffff0000, v221
	v_and_b32_e32 v5, 0xffff0000, v43
	v_mul_f32_e32 v4, v4, v5
	v_cvt_pk_bf16_f32 v3, v3, v4
	global_store_dwordx4 v[50:51], v[0:3], off offset:128
	s_nop 1
	v_lshlrev_b32_e32 v0, 16, v36
	s_waitcnt lgkmcnt(0)
	v_lshlrev_b32_e32 v1, 16, v222
	v_mul_f32_e32 v0, v1, v0
	v_and_b32_e32 v1, 0xffff0000, v222
	v_and_b32_e32 v2, 0xffff0000, v36
	v_mul_f32_e32 v1, v1, v2
	v_cvt_pk_bf16_f32 v0, v0, v1
	v_lshlrev_b32_e32 v1, 16, v37
	v_lshlrev_b32_e32 v2, 16, v223
	v_mul_f32_e32 v1, v2, v1
	v_and_b32_e32 v2, 0xffff0000, v223
	v_and_b32_e32 v3, 0xffff0000, v37
	v_mul_f32_e32 v2, v2, v3
	v_cvt_pk_bf16_f32 v1, v1, v2
	v_lshlrev_b32_e32 v2, 16, v38
	v_lshlrev_b32_e32 v3, 16, v224
	v_mul_f32_e32 v2, v3, v2
	v_and_b32_e32 v3, 0xffff0000, v224
	v_and_b32_e32 v4, 0xffff0000, v38
	v_mul_f32_e32 v3, v3, v4
	v_cvt_pk_bf16_f32 v2, v2, v3
	v_lshlrev_b32_e32 v3, 16, v39
	v_lshlrev_b32_e32 v4, 16, v225
	v_mul_f32_e32 v3, v4, v3
	v_and_b32_e32 v4, 0xffff0000, v225
	v_and_b32_e32 v5, 0xffff0000, v39
	v_mul_f32_e32 v4, v4, v5
	v_cvt_pk_bf16_f32 v3, v3, v4
	global_store_dwordx4 v[52:53], v[0:3], off offset:128
	s_waitcnt vmcnt(7)
	s_nop 0
	v_lshlrev_b32_e32 v0, 16, v32
	s_waitcnt lgkmcnt(0)
	v_lshlrev_b32_e32 v1, 16, v226
	v_mul_f32_e32 v0, v1, v0
	v_and_b32_e32 v1, 0xffff0000, v226
	v_and_b32_e32 v2, 0xffff0000, v32
	v_mul_f32_e32 v1, v1, v2
	v_cvt_pk_bf16_f32 v0, v0, v1
	v_lshlrev_b32_e32 v1, 16, v33
	v_lshlrev_b32_e32 v2, 16, v227
	v_mul_f32_e32 v1, v2, v1
	v_and_b32_e32 v2, 0xffff0000, v227
	v_and_b32_e32 v3, 0xffff0000, v33
	v_mul_f32_e32 v2, v2, v3
	v_cvt_pk_bf16_f32 v1, v1, v2
	v_lshlrev_b32_e32 v2, 16, v34
	v_lshlrev_b32_e32 v3, 16, v228
	v_mul_f32_e32 v2, v3, v2
	v_and_b32_e32 v3, 0xffff0000, v228
	v_and_b32_e32 v4, 0xffff0000, v34
	v_mul_f32_e32 v3, v3, v4
	v_cvt_pk_bf16_f32 v2, v2, v3
	v_lshlrev_b32_e32 v3, 16, v35
	v_lshlrev_b32_e32 v4, 16, v229
	v_mul_f32_e32 v3, v4, v3
	v_and_b32_e32 v4, 0xffff0000, v229
	v_and_b32_e32 v5, 0xffff0000, v35
	v_mul_f32_e32 v4, v4, v5
	v_cvt_pk_bf16_f32 v3, v3, v4
	global_store_dwordx4 v[54:55], v[0:3], off offset:128
	s_waitcnt lgkmcnt(0)
	s_cbranch_vccnz .LBB0_1162
	s_waitcnt lgkmcnt(0)
	s_barrier
